# start skew: at the dispatch of the mix-in GEMM phase every second workgroup of an XCD sleeps ~1.7us so the unit-end store bursts of neighbouring CUs do not coincide
# speedup vs baseline: 1.0013x; 1.0013x over previous
.LBB0_13:
	s_cmp_eq_u32 s34, 5
	s_cselect_b32 s0, 2, 1
	v_writelane_b32 v253, s0, 60
	s_lshr_b32 s0, 0x4, s34
	s_bitcmp1_b32 s0, 0
	s_cbranch_scc0 .Lskew_next1
	v_readlane_b32 s0, v253, 39
	s_nop 3
	s_lshr_b32 s0, s0, 3
	s_and_b32 s0, s0, 1
	s_mul_i32 s0, s0, 2
.Lskew_loop1:
	s_cmp_eq_u32 s0, 0
	s_cbranch_scc1 .Lskew_next1
	s_sleep 32
	s_sub_u32 s0, s0, 1
	s_branch .Lskew_loop1
.Lskew_next1:
	s_mul_hi_i32 s0, s3, 0x2aaaaaab
	s_lshr_b32 s1, s0, 31
	s_ashr_i32 s0, s0, 1
	s_add_i32 s0, s0, s1
	v_readlane_b32 s4, v250, 0
	s_bitcmp0_b32 s0, 0
	v_readlane_b32 s6, v250, 2
	v_readlane_b32 s11, v250, 7
	v_readlane_b32 s1, v250, 41
	v_readlane_b32 s7, v250, 3
	v_readlane_b32 s10, v250, 6
	v_readlane_b32 s2, v250, 42
	s_cselect_b32 s11, s6, s1
	v_readlane_b32 s5, v250, 1
	s_cselect_b32 s10, s7, s2
	s_cselect_b32 s36, s1, s6
	s_cselect_b32 s37, s2, s7
	s_add_u32 s4, s11, 0x18a0000
	s_addc_u32 s5, s10, 0
	v_writelane_b32 v253, s4, 61
	s_ashr_i32 s1, s0, 31
	s_mul_hi_i32 s2, s0, 0x1600
	v_writelane_b32 v253, s5, 62
	s_mul_i32 s4, s0, 0x1600
	v_readlane_b32 s16, v253, 7
	v_readlane_b32 s24, v253, 15
	v_readlane_b32 s30, v253, 21
	v_readlane_b32 s25, v253, 16
	v_readlane_b32 s31, v253, 22
	s_add_u32 s30, s24, s4
	s_mul_i32 s4, s0, 0x180
	s_addc_u32 s31, s25, s2
	s_ashr_i32 s5, s4, 31
	v_readlane_b32 s17, v253, 8
	v_readlane_b32 s18, v253, 9
	v_readlane_b32 s19, v253, 10
	v_readlane_b32 s20, v253, 11
	v_readlane_b32 s21, v253, 12
	v_readlane_b32 s22, v253, 13
	v_readlane_b32 s23, v253, 14
	v_readlane_b32 s26, v253, 17
	v_readlane_b32 s27, v253, 18
	v_readlane_b32 s28, v253, 19
	v_readlane_b32 s29, v253, 20
	v_writelane_b32 v253, s4, 63
	s_mul_hi_i32 s2, s0, 0xc00
	v_readlane_b32 s52, v253, 23
	v_writelane_b32 v254, s5, 0
	s_lshl_b64 s[4:5], s[4:5], 2
	v_readlane_b32 s58, v253, 29
	v_readlane_b32 s59, v253, 30
	s_add_u32 s6, s58, s4
	s_addc_u32 s7, s59, s5
	v_readlane_b32 s60, v253, 31
	v_writelane_b32 v254, s6, 1
	v_readlane_b32 s61, v253, 32
	v_readlane_b32 s62, v253, 33
	v_writelane_b32 v254, s7, 2
	s_add_u32 s6, s60, s4
	s_addc_u32 s7, s61, s5
	v_writelane_b32 v254, s6, 3
	v_readlane_b32 s63, v253, 34
	v_readlane_b32 s64, v253, 35
	v_writelane_b32 v254, s7, 4
	s_add_u32 s6, s62, s4
	s_addc_u32 s7, s63, s5
	v_writelane_b32 v254, s6, 5
	v_readlane_b32 s65, v253, 36
	v_readlane_b32 s56, v253, 27
	v_writelane_b32 v254, s7, 6
	s_add_u32 s6, s64, s4
	s_addc_u32 s7, s65, s5
	v_writelane_b32 v254, s6, 7
	v_readlane_b32 s57, v253, 28
	v_readlane_b32 s8, v250, 4
	v_writelane_b32 v254, s7, 8
	s_add_u32 s6, s22, s4
	s_addc_u32 s7, s23, s5
	v_writelane_b32 v254, s6, 9
	v_readlane_b32 s9, v250, 5
	v_readlane_b32 s68, v253, 42
	v_writelane_b32 v254, s7, 10
	s_mul_i32 s6, s0, 0xc00
	s_add_u32 s6, s16, s6
	s_addc_u32 s7, s17, s2
	v_writelane_b32 v254, s6, 11
	v_readlane_b32 s74, v253, 48
	v_readlane_b32 s75, v253, 49
	v_writelane_b32 v254, s7, 12
	s_lshl_b32 s6, s0, 8
	s_ashr_i32 s7, s6, 31
	s_lshl_b64 s[6:7], s[6:7], 2
	s_add_u32 s6, s18, s6
	s_addc_u32 s7, s19, s7
	v_writelane_b32 v254, s6, 13
	s_add_u32 s4, s56, s4
	s_addc_u32 s5, s57, s5
	v_writelane_b32 v254, s7, 14
	s_add_i32 s2, s0, 1
	v_writelane_b32 v254, s4, 15
	s_cmp_lt_i32 s3, 36
	v_readlane_b32 s80, v253, 54
	v_writelane_b32 v254, s5, 16
	s_cselect_b64 s[4:5], -1, 0
	s_ashr_i32 s3, s2, 31
	s_lshl_b32 s6, s2, 10
	s_ashr_i32 s7, s6, 31
	s_lshl_b64 s[8:9], s[2:3], 22
	s_add_u32 s12, s36, 0x1ca0000
	s_addc_u32 s13, s37, 0
	v_writelane_b32 v254, s12, 17
	s_mul_hi_i32 s3, s2, 0xe80000
	v_readlane_b32 s81, v253, 55
	v_writelane_b32 v254, s13, 18
	s_add_u32 s12, s36, 0x18a0000
	s_addc_u32 s13, s37, 0
	v_writelane_b32 v254, s12, 19
	v_readlane_b32 s78, v253, 52
	v_readlane_b32 s79, v253, 53
	v_writelane_b32 v254, s13, 20
	s_add_u32 s12, s36, 0x1080000
	s_addc_u32 s13, s37, 0
	v_writelane_b32 v254, s12, 21
	v_readlane_b32 s76, v253, 50
	v_readlane_b32 s77, v253, 51
	v_writelane_b32 v254, s13, 22
	s_add_u32 s12, s36, 0x29a0000
	s_addc_u32 s13, s37, 0
	v_writelane_b32 v254, s12, 23
	v_readlane_b32 s66, v253, 37
	v_readlane_b32 s67, v253, 38
	v_writelane_b32 v254, s13, 24
	s_add_u32 s12, s36, 0xb00000
	s_addc_u32 s13, s37, 0
	v_writelane_b32 v254, s12, 25
	v_readlane_b32 s53, v253, 24
	v_readlane_b32 s54, v253, 25
	v_writelane_b32 v254, s13, 26
	s_add_u32 s12, s36, 0x1ea0000
	s_addc_u32 s13, s37, 0
	v_writelane_b32 v254, s12, 27
	v_readlane_b32 s55, v253, 26
	v_readlane_b32 s82, v253, 56
	v_writelane_b32 v254, s13, 28
	s_add_u32 s12, s74, s8
	s_addc_u32 s13, s75, s9
	v_writelane_b32 v254, s12, 29
	v_readlane_b32 s83, v253, 57
	s_mov_b32 s97, 0
	v_writelane_b32 v254, s13, 30
	v_readlane_b32 s12, v252, 14
	v_readlane_b32 s26, v252, 28
	v_readlane_b32 s27, v252, 29
	s_add_u32 s8, s26, s8
	s_addc_u32 s9, s27, s9
	v_writelane_b32 v254, s8, 31
	v_readlane_b32 s24, v252, 26
	v_readlane_b32 s25, v252, 27
	v_writelane_b32 v254, s9, 32
	s_mul_i32 s8, s2, 0xe80000
	s_add_u32 s8, s24, s8
	s_addc_u32 s9, s25, s3
	v_readlane_b32 s22, v252, 24
	v_writelane_b32 v254, s8, 33
	s_lshl_b64 s[6:7], s[6:7], 2
	v_readlane_b32 s23, v252, 25
	v_writelane_b32 v254, s9, 34
	s_add_u32 s8, s22, s6
	s_addc_u32 s9, s23, s7
	v_writelane_b32 v254, s8, 35
	v_readlane_b32 s13, v252, 15
	s_mul_hi_i32 s3, s2, 0xb00000
	v_writelane_b32 v254, s9, 36
	s_mul_i32 s8, s2, 0xb00000
	s_add_u32 s12, s80, s8
	v_readlane_b32 s20, v252, 22
	s_addc_u32 s13, s81, s3
	v_readlane_b32 s21, v252, 23
	v_writelane_b32 v254, s12, 37
	s_add_u32 s8, s20, s8
	s_addc_u32 s9, s21, s3
	v_writelane_b32 v254, s13, 38
	v_writelane_b32 v254, s8, 39
	s_mul_hi_i32 s3, s2, 0x1600000
	v_readlane_b32 s18, v252, 20
	v_writelane_b32 v254, s9, 40
	s_mul_i32 s8, s2, 0x1600000
	s_add_u32 s12, s78, s8
	s_addc_u32 s13, s79, s3
	v_writelane_b32 v254, s12, 41
	v_readlane_b32 s19, v252, 21
	v_readlane_b32 s16, v252, 18
	v_writelane_b32 v254, s13, 42
	s_add_u32 s12, s76, s6
	s_addc_u32 s13, s77, s7
	v_writelane_b32 v254, s12, 43
	s_add_u32 s8, s18, s8
	s_addc_u32 s9, s19, s3
	v_writelane_b32 v254, s13, 44
	v_writelane_b32 v254, s8, 45
	v_readlane_b32 s17, v252, 19
	v_readlane_b32 s18, v253, 58
	v_writelane_b32 v254, s9, 46
	s_add_u32 s8, s16, s6
	s_addc_u32 s9, s17, s7
	v_writelane_b32 v254, s8, 47
	s_add_u32 s3, s11, 0x1ca0000
	v_readlane_b32 s19, v253, 59
	v_writelane_b32 v254, s9, 48
	v_writelane_b32 v254, s3, 49
	s_addc_u32 s3, s10, 0
	v_writelane_b32 v254, s3, 50
	s_lshl_b64 s[0:1], s[0:1], 22
	v_readlane_b32 s3, v250, 62
	s_add_u32 s3, s3, s0
	v_readlane_b32 s69, v253, 43
	v_writelane_b32 v254, s3, 51
	v_readlane_b32 s3, v250, 63
	s_addc_u32 s3, s3, s1
	v_readlane_b32 s70, v253, 44
	v_writelane_b32 v254, s3, 52
	v_readlane_b32 s3, v251, 0
	s_add_u32 s3, s3, s0
	v_readlane_b32 s71, v253, 45
	v_writelane_b32 v254, s3, 53
	v_readlane_b32 s3, v251, 1
	s_addc_u32 s3, s3, s1
	v_readlane_b32 s72, v253, 46
	v_writelane_b32 v254, s3, 54
	s_add_u32 s3, s11, 0x1aa0000
	v_writelane_b32 v254, s3, 55
	s_addc_u32 s3, s10, 0
	s_add_u32 s8, s11, 0x1800000
	v_writelane_b32 v254, s3, 56
	s_addc_u32 s9, s10, 0
	v_writelane_b32 v254, s8, 57
	s_mov_b32 s3, 0x29a0000
	v_readlane_b32 s73, v253, 47
	v_writelane_b32 v254, s9, 58
	s_add_u32 s8, s30, 0x1200
	v_writelane_b32 v254, s30, 59
	s_addc_u32 s9, s31, 0
	v_readlane_b32 s14, v252, 16
	v_writelane_b32 v254, s31, 60
	v_writelane_b32 v254, s8, 61
	v_readlane_b32 s15, v252, 17
	s_nop 0
	v_writelane_b32 v254, s9, 62
	s_add_u32 s8, s11, 0x1080000
	s_addc_u32 s9, s10, 0
	s_cmp_eq_u32 s34, 1
	v_writelane_b32 v254, s8, 63
	s_cselect_b32 s3, 0xb00000, s3
	s_nop 0
	v_writelane_b32 v255, s9, 0
	s_add_u32 s8, s11, s3
	s_addc_u32 s9, s10, 0
	s_cmp_eq_u32 s34, 0
	v_writelane_b32 v255, s8, 1
	s_cselect_b32 s3, 0, 0x1ea0000
	s_nop 0
	v_writelane_b32 v255, s9, 2
	s_add_u32 s8, s11, s3
	v_writelane_b32 v255, s34, 3
	s_addc_u32 s9, s10, 0
	v_writelane_b32 v255, s8, 4
	s_mul_hi_i32 s3, s2, 0x18000
	s_nop 0
	v_writelane_b32 v255, s9, 5
	v_readlane_b32 s8, v253, 1
	v_readlane_b32 s9, v253, 2
	s_and_b64 s[4:5], s[4:5], s[8:9]
	v_writelane_b32 v255, s4, 6
	s_nop 1
	v_writelane_b32 v255, s5, 7
	s_add_u32 s4, s66, s6
	s_addc_u32 s5, s67, s7
	v_writelane_b32 v255, s4, 8
	s_nop 1
	v_writelane_b32 v255, s5, 9
	s_mul_i32 s4, s2, 0x18000
	s_add_u32 s6, s28, s4
	s_addc_u32 s7, s29, s3
	v_writelane_b32 v255, s6, 10
	s_add_u32 s4, s52, s4
	s_addc_u32 s5, s53, s3
	v_writelane_b32 v255, s7, 11
	s_mul_hi_i32 s3, s2, 0x30000
	s_mul_i32 s2, s2, 0x30000
	v_writelane_b32 v255, s4, 12
	s_add_u32 s2, s54, s2
	s_addc_u32 s3, s55, s3
	v_writelane_b32 v255, s5, 13
	v_writelane_b32 v255, s2, 14
	s_nop 1
	v_writelane_b32 v255, s3, 15
	v_readlane_b32 s2, v252, 49
	s_add_u32 s2, s2, s0
	v_readlane_b32 s0, v252, 50
	s_addc_u32 s3, s0, s1
	v_writelane_b32 v255, s2, 16
	s_add_u32 s0, s36, 0x1aa0000
	s_addc_u32 s1, s37, 0
	v_writelane_b32 v255, s3, 17
	v_writelane_b32 v255, s0, 18
	s_nop 1
	v_writelane_b32 v255, s1, 19
	s_add_u32 s0, s36, 0x1800000
	v_writelane_b32 v255, s36, 20
	s_addc_u32 s1, s37, 0
	s_nop 0
	v_writelane_b32 v255, s37, 21
	v_writelane_b32 v255, s0, 22
	s_nop 1
	v_writelane_b32 v255, s1, 23
	v_writelane_b32 v255, s38, 24
	s_branch .LBB0_17
